# adds nt (streaming) policy on G5 ACT stores
# speedup vs baseline: 1.0248x; 1.0035x over previous
.LBB0_1268:
	s_or_b64 exec, exec, s[56:57]
	v_pk_mul_f32 v[152:153], v[118:119], v[196:197] op_sel_hi:[1,0]
	v_pk_mul_f32 v[118:119], v[122:123], v[192:193] op_sel_hi:[1,0]
	v_pk_mul_f32 v[122:123], v[108:109], v[192:193] op_sel_hi:[1,0]
	v_mov_b32_e32 v108, v188
	v_mov_b32_e32 v109, v188
	v_mov_b32_e32 v189, v188
	v_pk_mul_f32 v[156:157], v[114:115], v[196:197] op_sel_hi:[1,0]
	v_pk_mul_f32 v[114:115], v[126:127], v[192:193] op_sel_hi:[1,0]
	v_pk_mul_f32 v[126:127], v[104:105], v[192:193] op_sel_hi:[1,0]
	v_pk_mul_f32 v[104:105], v[102:103], v[108:109]
	v_pk_mul_f32 v[102:103], v[72:73], v[194:195] op_sel_hi:[1,0]
	v_pk_mul_f32 v[72:73], v[84:85], v[190:191] op_sel_hi:[1,0]
	v_pk_mul_f32 v[84:85], v[58:59], v[190:191] op_sel_hi:[1,0]
	v_pk_mul_f32 v[58:59], v[70:71], v[186:187] op_sel_hi:[1,0]
	v_mov_b32_e32 v70, v150
	v_mov_b32_e32 v71, v151
	v_pk_mul_f32 v[130:131], v[130:131], v[196:197] op_sel_hi:[1,0]
	v_pk_mul_f32 v[158:159], v[112:113], v[196:197] op_sel_hi:[1,0]
	v_pk_mul_f32 v[112:113], v[124:125], v[192:193] op_sel_hi:[1,0]
	v_pk_mul_f32 v[124:125], v[106:107], v[192:193] op_sel_hi:[1,0]
	v_pk_mul_f32 v[106:107], v[100:101], v[188:189]
	v_pk_mul_f32 v[100:101], v[74:75], v[194:195] op_sel_hi:[1,0]
	v_pk_mul_f32 v[74:75], v[86:87], v[190:191] op_sel_hi:[1,0]
	v_pk_mul_f32 v[86:87], v[56:57], v[190:191] op_sel_hi:[1,0]
	v_pk_mul_f32 v[56:57], v[68:69], v[186:187] op_sel_hi:[1,0]
	v_mov_b32_e32 v68, v148
	v_mov_b32_e32 v69, v149
	v_mov_b32_dpp v70, v70 row_ror:1 row_mask:0xf bank_mask:0xf
	v_mov_b32_dpp v71, v71 row_ror:1 row_mask:0xf bank_mask:0xf
	v_pk_mul_f32 v[128:129], v[128:129], v[196:197] op_sel_hi:[1,0]
	v_mov_b32_dpp v68, v68 row_ror:1 row_mask:0xf bank_mask:0xf
	v_mov_b32_dpp v69, v69 row_ror:1 row_mask:0xf bank_mask:0xf
	v_mov_b32_dpp v70, v130 row_shr:1 row_mask:0xf bank_mask:0xf
	v_mov_b32_dpp v150, v150 row_ror:2 row_mask:0xf bank_mask:0xf
	v_mov_b32_dpp v71, v131 row_shr:1 row_mask:0xf bank_mask:0xf
	v_mov_b32_dpp v151, v151 row_ror:2 row_mask:0xf bank_mask:0xf
	v_pk_fma_f32 v[160:161], v[130:131], v[38:39], v[42:43]
	v_mov_b32_dpp v68, v128 row_shr:1 row_mask:0xf bank_mask:0xf
	v_mov_b32_dpp v148, v148 row_ror:2 row_mask:0xf bank_mask:0xf
	v_mov_b32_dpp v69, v129 row_shr:1 row_mask:0xf bank_mask:0xf
	v_mov_b32_dpp v149, v149 row_ror:2 row_mask:0xf bank_mask:0xf
	v_mov_b32_dpp v150, v130 row_shr:2 row_mask:0xf bank_mask:0xf
	v_mov_b32_dpp v151, v131 row_shr:2 row_mask:0xf bank_mask:0xf
	v_pk_fma_f32 v[162:163], v[128:129], v[36:37], v[40:41]
	v_pk_fma_f32 v[70:71], v[34:35], v[70:71], v[160:161]
	v_mov_b32_dpp v148, v128 row_shr:2 row_mask:0xf bank_mask:0xf
	v_mov_b32_dpp v149, v129 row_shr:2 row_mask:0xf bank_mask:0xf
	v_pk_fma_f32 v[68:69], v[32:33], v[68:69], v[162:163]
	v_pk_fma_f32 v[70:71], v[30:31], v[150:151], v[70:71]
	v_pk_mul_f32 v[154:155], v[116:117], v[196:197] op_sel_hi:[1,0]
	v_pk_mul_f32 v[116:117], v[120:121], v[192:193] op_sel_hi:[1,0]
	v_pk_mul_f32 v[120:121], v[110:111], v[192:193] op_sel_hi:[1,0]
	v_pk_mul_f32 v[108:109], v[98:99], v[108:109]
	v_pk_mul_f32 v[110:111], v[96:97], v[188:189]
	v_pk_mul_f32 v[96:97], v[78:79], v[194:195] op_sel_hi:[1,0]
	v_pk_mul_f32 v[98:99], v[76:77], v[194:195] op_sel_hi:[1,0]
	v_pk_mul_f32 v[78:79], v[82:83], v[190:191] op_sel_hi:[1,0]
	v_pk_mul_f32 v[76:77], v[80:81], v[190:191] op_sel_hi:[1,0]
	v_pk_mul_f32 v[80:81], v[62:63], v[190:191] op_sel_hi:[1,0]
	v_pk_mul_f32 v[82:83], v[60:61], v[190:191] op_sel_hi:[1,0]
	v_pk_mul_f32 v[62:63], v[66:67], v[186:187] op_sel_hi:[1,0]
	v_pk_mul_f32 v[60:61], v[64:65], v[186:187] op_sel_hi:[1,0]
	v_mov_b32_e32 v64, v182
	v_mov_b32_e32 v65, v182
	v_mov_b32_e32 v66, v146
	v_mov_b32_e32 v67, v147
	v_pk_fma_f32 v[68:69], v[28:29], v[148:149], v[68:69]
	v_pk_mul_f32 v[148:149], v[70:71], v[70:71]
	v_pk_mul_f32 v[134:135], v[134:135], v[196:197] op_sel_hi:[1,0]
	v_pk_mul_f32 v[46:47], v[46:47], v[64:65]
	v_pk_mul_f32 v[2:3], v[2:3], v[64:65]
	v_mov_b32_e32 v64, v144
	v_mov_b32_e32 v65, v145
	v_mov_b32_dpp v66, v66 row_ror:1 row_mask:0xf bank_mask:0xf
	v_mov_b32_dpp v67, v67 row_ror:1 row_mask:0xf bank_mask:0xf
	v_pk_mul_f32 v[150:151], v[68:69], v[68:69]
	v_pk_fma_f32 v[148:149], v[148:149], s[30:31], 1.0 op_sel_hi:[1,0,0]
	v_pk_mul_f32 v[132:133], v[132:133], v[196:197] op_sel_hi:[1,0]
	v_mov_b32_dpp v64, v64 row_ror:1 row_mask:0xf bank_mask:0xf
	v_mov_b32_dpp v65, v65 row_ror:1 row_mask:0xf bank_mask:0xf
	v_mov_b32_dpp v66, v134 row_shr:1 row_mask:0xf bank_mask:0xf
	v_mov_b32_dpp v146, v146 row_ror:2 row_mask:0xf bank_mask:0xf
	v_mov_b32_dpp v67, v135 row_shr:1 row_mask:0xf bank_mask:0xf
	v_mov_b32_dpp v147, v147 row_ror:2 row_mask:0xf bank_mask:0xf
	v_pk_fma_f32 v[150:151], v[150:151], s[30:31], 1.0 op_sel_hi:[1,0,0]
	v_pk_mul_f32 v[148:149], v[70:71], v[148:149]
	v_pk_mul_f32 v[70:71], v[156:157], v[70:71]
	v_pk_fma_f32 v[156:157], v[134:135], v[22:23], v[26:27]
	v_mov_b32_dpp v64, v132 row_shr:1 row_mask:0xf bank_mask:0xf
	v_mov_b32_dpp v144, v144 row_ror:2 row_mask:0xf bank_mask:0xf
	v_mov_b32_dpp v65, v133 row_shr:1 row_mask:0xf bank_mask:0xf
	v_mov_b32_dpp v145, v145 row_ror:2 row_mask:0xf bank_mask:0xf
	v_mov_b32_dpp v146, v134 row_shr:2 row_mask:0xf bank_mask:0xf
	v_mov_b32_dpp v147, v135 row_shr:2 row_mask:0xf bank_mask:0xf
	v_pk_mul_f32 v[150:151], v[68:69], v[150:151]
	v_pk_mul_f32 v[68:69], v[158:159], v[68:69]
	v_pk_fma_f32 v[158:159], v[132:133], v[20:21], v[24:25]
	v_pk_fma_f32 v[66:67], v[18:19], v[66:67], v[156:157]
	v_mov_b32_dpp v144, v132 row_shr:2 row_mask:0xf bank_mask:0xf
	v_mov_b32_dpp v145, v133 row_shr:2 row_mask:0xf bank_mask:0xf
	v_pk_fma_f32 v[64:65], v[16:17], v[64:65], v[158:159]
	v_pk_fma_f32 v[66:67], v[14:15], v[146:147], v[66:67]
	v_pk_fma_f32 v[64:65], v[12:13], v[144:145], v[64:65]
	v_pk_mul_f32 v[144:145], v[66:67], v[66:67]
	v_pk_mul_f32 v[146:147], v[64:65], v[64:65]
	v_pk_fma_f32 v[144:145], v[144:145], s[30:31], 1.0 op_sel_hi:[1,0,0]
	v_pk_fma_f32 v[146:147], v[146:147], s[30:31], 1.0 op_sel_hi:[1,0,0]
	v_pk_mul_f32 v[144:145], v[66:67], v[144:145]
	v_pk_mul_f32 v[148:149], v[148:149], s[34:35] op_sel_hi:[1,0]
	v_pk_mul_f32 v[150:151], v[150:151], s[34:35] op_sel_hi:[1,0]
	v_pk_mul_f32 v[146:147], v[64:65], v[146:147]
	v_pk_mul_f32 v[144:145], v[144:145], s[34:35] op_sel_hi:[1,0]
	v_exp_f32_e32 v150, v150
	v_exp_f32_e32 v148, v148
	v_exp_f32_e32 v149, v149
	v_exp_f32_e32 v151, v151
	v_pk_mul_f32 v[146:147], v[146:147], s[34:35] op_sel_hi:[1,0]
	v_exp_f32_e32 v144, v144
	v_exp_f32_e32 v145, v145
	v_exp_f32_e32 v146, v146
	v_exp_f32_e32 v147, v147
	v_pk_add_f32 v[148:149], v[148:149], 1.0 op_sel_hi:[1,0]
	v_pk_add_f32 v[150:151], v[150:151], 1.0 op_sel_hi:[1,0]
	v_pk_add_f32 v[144:145], v[144:145], 1.0 op_sel_hi:[1,0]
	v_rcp_f32_e32 v150, v150
	v_rcp_f32_e32 v151, v151
	v_rcp_f32_e32 v148, v148
	v_rcp_f32_e32 v149, v149
	v_pk_add_f32 v[146:147], v[146:147], 1.0 op_sel_hi:[1,0]
	v_rcp_f32_e32 v144, v144
	v_rcp_f32_e32 v145, v145
	v_rcp_f32_e32 v146, v146
	v_rcp_f32_e32 v147, v147
	v_pk_mul_f32 v[66:67], v[152:153], v[66:67]
	v_pk_mul_f32 v[70:71], v[70:71], v[148:149]
	v_pk_mul_f32 v[68:69], v[68:69], v[150:151]
	v_pk_mul_f32 v[64:65], v[154:155], v[64:65]
	v_pk_mul_f32 v[144:145], v[66:67], v[144:145]
	v_pk_mul_f32 v[64:65], v[64:65], v[146:147]
	v_pk_fma_f32 v[146:147], v[118:119], v[38:39], v[42:43]
	v_cvt_pk_bf16_f32 v66, v64, v65
	v_cvt_pk_bf16_f32 v67, v144, v145
	v_cvt_pk_bf16_f32 v68, v68, v69
	v_cvt_pk_bf16_f32 v69, v70, v71
	v_mov_b32_e32 v70, v128
	v_mov_b32_e32 v71, v129
	v_mov_b32_e32 v144, v130
	v_mov_b32_e32 v145, v131
	v_mov_b32_dpp v70, v70 row_ror:1 row_mask:0xf bank_mask:0xf
	v_mov_b32_dpp v71, v71 row_ror:1 row_mask:0xf bank_mask:0xf
	v_mov_b32_dpp v144, v144 row_ror:1 row_mask:0xf bank_mask:0xf
	v_mov_b32_dpp v145, v145 row_ror:1 row_mask:0xf bank_mask:0xf
	v_mov_b32_dpp v70, v116 row_shr:1 row_mask:0xf bank_mask:0xf
	v_mov_b32_dpp v128, v128 row_ror:2 row_mask:0xf bank_mask:0xf
	v_mov_b32_dpp v71, v117 row_shr:1 row_mask:0xf bank_mask:0xf
	v_mov_b32_dpp v129, v129 row_ror:2 row_mask:0xf bank_mask:0xf
	v_mov_b32_dpp v144, v118 row_shr:1 row_mask:0xf bank_mask:0xf
	v_mov_b32_dpp v130, v130 row_ror:2 row_mask:0xf bank_mask:0xf
	v_mov_b32_dpp v145, v119 row_shr:1 row_mask:0xf bank_mask:0xf
	v_mov_b32_dpp v131, v131 row_ror:2 row_mask:0xf bank_mask:0xf
	v_pk_fma_f32 v[148:149], v[116:117], v[36:37], v[40:41]
	v_mov_b32_dpp v128, v116 row_shr:2 row_mask:0xf bank_mask:0xf
	v_mov_b32_dpp v129, v117 row_shr:2 row_mask:0xf bank_mask:0xf
	v_mov_b32_dpp v130, v118 row_shr:2 row_mask:0xf bank_mask:0xf
	v_mov_b32_dpp v131, v119 row_shr:2 row_mask:0xf bank_mask:0xf
	v_pk_fma_f32 v[144:145], v[34:35], v[144:145], v[146:147]
	v_pk_fma_f32 v[70:71], v[32:33], v[70:71], v[148:149]
	v_pk_fma_f32 v[130:131], v[30:31], v[130:131], v[144:145]
	v_pk_fma_f32 v[70:71], v[28:29], v[128:129], v[70:71]
	v_pk_mul_f32 v[128:129], v[130:131], v[130:131]
	v_pk_mul_f32 v[144:145], v[70:71], v[70:71]
	v_pk_fma_f32 v[128:129], v[128:129], s[30:31], 1.0 op_sel_hi:[1,0,0]
	v_pk_fma_f32 v[144:145], v[144:145], s[30:31], 1.0 op_sel_hi:[1,0,0]
	v_pk_mul_f32 v[128:129], v[130:131], v[128:129]
	v_pk_mul_f32 v[144:145], v[70:71], v[144:145]
	v_pk_mul_f32 v[128:129], v[128:129], s[34:35] op_sel_hi:[1,0]
	v_pk_mul_f32 v[144:145], v[144:145], s[34:35] op_sel_hi:[1,0]
	v_add_lshl_u32 v64, v210, v184, 1
	v_exp_f32_e32 v144, v144
	v_exp_f32_e32 v128, v128
	v_exp_f32_e32 v129, v129
	v_exp_f32_e32 v145, v145
	v_add_u32_e32 v65, 0x16000, v64
	global_store_dwordx4 v65, v[66:69], s[18:19] nt
	v_pk_mul_f32 v[124:125], v[124:125], v[130:131]
	v_pk_mul_f32 v[70:71], v[126:127], v[70:71]
	v_mov_b32_e32 v66, v132
	v_mov_b32_e32 v67, v133
	v_mov_b32_e32 v68, v134
	v_mov_b32_e32 v69, v135
	v_mov_b32_dpp v66, v66 row_ror:1 row_mask:0xf bank_mask:0xf
	v_mov_b32_dpp v67, v67 row_ror:1 row_mask:0xf bank_mask:0xf
	v_mov_b32_dpp v68, v68 row_ror:1 row_mask:0xf bank_mask:0xf
	v_mov_b32_dpp v69, v69 row_ror:1 row_mask:0xf bank_mask:0xf
	v_mov_b32_dpp v66, v112 row_shr:1 row_mask:0xf bank_mask:0xf
	v_mov_b32_dpp v132, v132 row_ror:2 row_mask:0xf bank_mask:0xf
	v_mov_b32_dpp v67, v113 row_shr:1 row_mask:0xf bank_mask:0xf
	v_mov_b32_dpp v133, v133 row_ror:2 row_mask:0xf bank_mask:0xf
	v_mov_b32_dpp v68, v114 row_shr:1 row_mask:0xf bank_mask:0xf
	v_mov_b32_dpp v134, v134 row_ror:2 row_mask:0xf bank_mask:0xf
	v_mov_b32_dpp v69, v115 row_shr:1 row_mask:0xf bank_mask:0xf
	v_mov_b32_dpp v135, v135 row_ror:2 row_mask:0xf bank_mask:0xf
	v_pk_add_f32 v[126:127], v[128:129], 1.0 op_sel_hi:[1,0]
	v_pk_add_f32 v[128:129], v[144:145], 1.0 op_sel_hi:[1,0]
	v_pk_fma_f32 v[130:131], v[114:115], v[22:23], v[26:27]
	v_pk_fma_f32 v[144:145], v[112:113], v[20:21], v[24:25]
	v_mov_b32_dpp v132, v112 row_shr:2 row_mask:0xf bank_mask:0xf
	v_mov_b32_dpp v133, v113 row_shr:2 row_mask:0xf bank_mask:0xf
	v_mov_b32_dpp v134, v114 row_shr:2 row_mask:0xf bank_mask:0xf
	v_mov_b32_dpp v135, v115 row_shr:2 row_mask:0xf bank_mask:0xf
	v_pk_fma_f32 v[68:69], v[18:19], v[68:69], v[130:131]
	v_pk_fma_f32 v[66:67], v[16:17], v[66:67], v[144:145]
	v_pk_fma_f32 v[68:69], v[14:15], v[134:135], v[68:69]
	v_pk_fma_f32 v[66:67], v[12:13], v[132:133], v[66:67]
	v_pk_mul_f32 v[130:131], v[68:69], v[68:69]
	v_pk_mul_f32 v[132:133], v[66:67], v[66:67]
	v_pk_fma_f32 v[130:131], v[130:131], s[30:31], 1.0 op_sel_hi:[1,0,0]
	v_pk_fma_f32 v[132:133], v[132:133], s[30:31], 1.0 op_sel_hi:[1,0,0]
	v_pk_mul_f32 v[130:131], v[68:69], v[130:131]
	v_pk_mul_f32 v[132:133], v[66:67], v[132:133]
	v_pk_mul_f32 v[130:131], v[130:131], s[34:35] op_sel_hi:[1,0]
	v_pk_mul_f32 v[132:133], v[132:133], s[34:35] op_sel_hi:[1,0]
	v_rcp_f32_e32 v128, v128
	v_rcp_f32_e32 v129, v129
	v_rcp_f32_e32 v126, v126
	v_rcp_f32_e32 v127, v127
	v_exp_f32_e32 v132, v132
	v_exp_f32_e32 v130, v130
	v_exp_f32_e32 v131, v131
	v_exp_f32_e32 v133, v133
	v_pk_mul_f32 v[124:125], v[124:125], v[126:127]
	v_pk_mul_f32 v[70:71], v[70:71], v[128:129]
	v_pk_add_f32 v[126:127], v[130:131], 1.0 op_sel_hi:[1,0]
	v_pk_add_f32 v[128:129], v[132:133], 1.0 op_sel_hi:[1,0]
	v_rcp_f32_e32 v126, v126
	v_rcp_f32_e32 v128, v128
	v_rcp_f32_e32 v127, v127
	v_rcp_f32_e32 v129, v129
	v_pk_mul_f32 v[68:69], v[120:121], v[68:69]
	v_pk_mul_f32 v[66:67], v[122:123], v[66:67]
	v_pk_mul_f32 v[68:69], v[68:69], v[126:127]
	v_pk_mul_f32 v[66:67], v[66:67], v[128:129]
	v_mov_b32_e32 v120, v118
	v_cvt_pk_bf16_f32 v66, v66, v67
	v_cvt_pk_bf16_f32 v67, v68, v69
	v_cvt_pk_bf16_f32 v68, v70, v71
	v_mov_b32_e32 v70, v116
	v_mov_b32_e32 v71, v117
	v_mov_b32_e32 v121, v119
	v_mov_b32_dpp v70, v70 row_ror:1 row_mask:0xf bank_mask:0xf
	v_mov_b32_dpp v71, v71 row_ror:1 row_mask:0xf bank_mask:0xf
	v_mov_b32_dpp v120, v120 row_ror:1 row_mask:0xf bank_mask:0xf
	v_mov_b32_dpp v121, v121 row_ror:1 row_mask:0xf bank_mask:0xf
	v_cvt_pk_bf16_f32 v69, v124, v125
	v_mov_b32_dpp v70, v140 row_shr:1 row_mask:0xf bank_mask:0xf
	v_mov_b32_dpp v116, v116 row_ror:2 row_mask:0xf bank_mask:0xf
	v_mov_b32_dpp v71, v141 row_shr:1 row_mask:0xf bank_mask:0xf
	v_mov_b32_dpp v117, v117 row_ror:2 row_mask:0xf bank_mask:0xf
	v_mov_b32_dpp v120, v142 row_shr:1 row_mask:0xf bank_mask:0xf
	v_mov_b32_dpp v118, v118 row_ror:2 row_mask:0xf bank_mask:0xf
	v_mov_b32_dpp v121, v143 row_shr:1 row_mask:0xf bank_mask:0xf
	v_mov_b32_dpp v119, v119 row_ror:2 row_mask:0xf bank_mask:0xf
	v_pk_fma_f32 v[122:123], v[142:143], v[38:39], v[42:43]
	v_pk_fma_f32 v[124:125], v[140:141], v[36:37], v[40:41]
	v_mov_b32_dpp v116, v140 row_shr:2 row_mask:0xf bank_mask:0xf
	v_mov_b32_dpp v117, v141 row_shr:2 row_mask:0xf bank_mask:0xf
	v_mov_b32_dpp v118, v142 row_shr:2 row_mask:0xf bank_mask:0xf
	v_mov_b32_dpp v119, v143 row_shr:2 row_mask:0xf bank_mask:0xf
	v_pk_fma_f32 v[120:121], v[34:35], v[120:121], v[122:123]
	v_pk_fma_f32 v[70:71], v[32:33], v[70:71], v[124:125]
	v_pk_fma_f32 v[118:119], v[30:31], v[118:119], v[120:121]
	v_pk_fma_f32 v[70:71], v[28:29], v[116:117], v[70:71]
	v_pk_mul_f32 v[116:117], v[118:119], v[118:119]
	v_pk_mul_f32 v[120:121], v[70:71], v[70:71]
	v_pk_fma_f32 v[116:117], v[116:117], s[30:31], 1.0 op_sel_hi:[1,0,0]
	v_pk_fma_f32 v[120:121], v[120:121], s[30:31], 1.0 op_sel_hi:[1,0,0]
	v_pk_mul_f32 v[116:117], v[118:119], v[116:117]
	v_pk_mul_f32 v[120:121], v[70:71], v[120:121]
	v_pk_mul_f32 v[116:117], v[116:117], s[34:35] op_sel_hi:[1,0]
	v_pk_mul_f32 v[120:121], v[120:121], s[34:35] op_sel_hi:[1,0]
	v_exp_f32_e32 v116, v116
	v_exp_f32_e32 v120, v120
	v_exp_f32_e32 v117, v117
	v_exp_f32_e32 v121, v121
	v_add_u32_e32 v65, 0x2c000, v64
	global_store_dwordx4 v65, v[66:69], s[18:19] nt
	v_pk_mul_f32 v[108:109], v[108:109], v[118:119]
	v_pk_mul_f32 v[70:71], v[110:111], v[70:71]
	v_mov_b32_e32 v66, v112
	v_mov_b32_e32 v67, v113
	v_mov_b32_e32 v68, v114
	v_mov_b32_e32 v69, v115
	v_mov_b32_dpp v66, v66 row_ror:1 row_mask:0xf bank_mask:0xf
	v_mov_b32_dpp v67, v67 row_ror:1 row_mask:0xf bank_mask:0xf
	v_mov_b32_dpp v68, v68 row_ror:1 row_mask:0xf bank_mask:0xf
	v_mov_b32_dpp v69, v69 row_ror:1 row_mask:0xf bank_mask:0xf
	v_mov_b32_dpp v66, v136 row_shr:1 row_mask:0xf bank_mask:0xf
	v_mov_b32_dpp v112, v112 row_ror:2 row_mask:0xf bank_mask:0xf
	v_mov_b32_dpp v67, v137 row_shr:1 row_mask:0xf bank_mask:0xf
	v_mov_b32_dpp v113, v113 row_ror:2 row_mask:0xf bank_mask:0xf
	v_mov_b32_dpp v68, v138 row_shr:1 row_mask:0xf bank_mask:0xf
	v_mov_b32_dpp v114, v114 row_ror:2 row_mask:0xf bank_mask:0xf
	v_mov_b32_dpp v69, v139 row_shr:1 row_mask:0xf bank_mask:0xf
	v_mov_b32_dpp v115, v115 row_ror:2 row_mask:0xf bank_mask:0xf
	v_pk_add_f32 v[110:111], v[116:117], 1.0 op_sel_hi:[1,0]
	v_pk_add_f32 v[116:117], v[120:121], 1.0 op_sel_hi:[1,0]
	v_pk_fma_f32 v[118:119], v[138:139], v[22:23], v[26:27]
	v_pk_fma_f32 v[120:121], v[136:137], v[20:21], v[24:25]
	v_mov_b32_dpp v112, v136 row_shr:2 row_mask:0xf bank_mask:0xf
	v_mov_b32_dpp v113, v137 row_shr:2 row_mask:0xf bank_mask:0xf
	v_mov_b32_dpp v114, v138 row_shr:2 row_mask:0xf bank_mask:0xf
	v_mov_b32_dpp v115, v139 row_shr:2 row_mask:0xf bank_mask:0xf
	v_pk_fma_f32 v[68:69], v[18:19], v[68:69], v[118:119]
	v_pk_fma_f32 v[66:67], v[16:17], v[66:67], v[120:121]
	v_pk_fma_f32 v[68:69], v[14:15], v[114:115], v[68:69]
	v_pk_fma_f32 v[66:67], v[12:13], v[112:113], v[66:67]
	v_pk_mul_f32 v[112:113], v[68:69], v[68:69]
	v_pk_mul_f32 v[114:115], v[66:67], v[66:67]
	v_pk_fma_f32 v[112:113], v[112:113], s[30:31], 1.0 op_sel_hi:[1,0,0]
	v_pk_fma_f32 v[114:115], v[114:115], s[30:31], 1.0 op_sel_hi:[1,0,0]
	v_pk_mul_f32 v[112:113], v[68:69], v[112:113]
	v_pk_mul_f32 v[114:115], v[66:67], v[114:115]
	v_pk_mul_f32 v[112:113], v[112:113], s[34:35] op_sel_hi:[1,0]
	v_pk_mul_f32 v[114:115], v[114:115], s[34:35] op_sel_hi:[1,0]
	v_rcp_f32_e32 v110, v110
	v_rcp_f32_e32 v111, v111
	v_exp_f32_e32 v114, v114
	v_exp_f32_e32 v112, v112
	v_exp_f32_e32 v113, v113
	v_exp_f32_e32 v115, v115
	v_pk_mul_f32 v[108:109], v[108:109], v[110:111]
	v_rcp_f32_e32 v116, v116
	v_pk_add_f32 v[110:111], v[112:113], 1.0 op_sel_hi:[1,0]
	v_pk_add_f32 v[112:113], v[114:115], 1.0 op_sel_hi:[1,0]
	v_rcp_f32_e32 v117, v117
	v_rcp_f32_e32 v112, v112
	v_rcp_f32_e32 v110, v110
	v_rcp_f32_e32 v111, v111
	v_rcp_f32_e32 v113, v113
	v_pk_mul_f32 v[68:69], v[104:105], v[68:69]
	v_pk_mul_f32 v[66:67], v[106:107], v[66:67]
	v_pk_mul_f32 v[70:71], v[70:71], v[116:117]
	v_pk_mul_f32 v[68:69], v[68:69], v[110:111]
	v_pk_mul_f32 v[66:67], v[66:67], v[112:113]
	v_add3_u32 v65, s73, v176, v209
	v_cvt_pk_bf16_f32 v66, v66, v67
	v_cvt_pk_bf16_f32 v67, v68, v69
	v_cvt_pk_bf16_f32 v68, v70, v71
	v_cvt_pk_bf16_f32 v69, v108, v109
	v_add_u32_e32 v70, 0x42000, v64
	ds_read_b128 v[104:107], v65 offset:2048
	global_store_dwordx4 v70, v[66:69], s[18:19] nt
	ds_read_b128 v[66:69], v65 offset:2064
	v_pk_mul_f32 v[90:91], v[90:91], v[194:195] op_sel_hi:[1,0]
	v_pk_mul_f32 v[88:89], v[88:89], v[194:195] op_sel_hi:[1,0]
	v_pk_fma_f32 v[114:115], v[90:91], v[38:39], v[42:43]
	v_pk_fma_f32 v[116:117], v[88:89], v[36:37], v[40:41]
	s_waitcnt lgkmcnt(0)
	v_mov_b32_e32 v110, v66
	v_mov_b32_e32 v111, v67
	v_mov_b32_e32 v112, v68
	v_mov_b32_e32 v113, v69
	v_mov_b32_dpp v110, v110 row_ror:1 row_mask:0xf bank_mask:0xf
	v_mov_b32_dpp v111, v111 row_ror:1 row_mask:0xf bank_mask:0xf
	v_mov_b32_dpp v112, v112 row_ror:1 row_mask:0xf bank_mask:0xf
	v_mov_b32_dpp v113, v113 row_ror:1 row_mask:0xf bank_mask:0xf
	v_mov_b32_dpp v110, v88 row_shr:1 row_mask:0xf bank_mask:0xf
	v_mov_b32_dpp v66, v66 row_ror:2 row_mask:0xf bank_mask:0xf
	v_mov_b32_dpp v111, v89 row_shr:1 row_mask:0xf bank_mask:0xf
	v_mov_b32_dpp v67, v67 row_ror:2 row_mask:0xf bank_mask:0xf
	v_mov_b32_dpp v112, v90 row_shr:1 row_mask:0xf bank_mask:0xf
	v_mov_b32_dpp v68, v68 row_ror:2 row_mask:0xf bank_mask:0xf
	v_mov_b32_dpp v113, v91 row_shr:1 row_mask:0xf bank_mask:0xf
	v_mov_b32_dpp v69, v69 row_ror:2 row_mask:0xf bank_mask:0xf
	v_mov_b32_dpp v66, v88 row_shr:2 row_mask:0xf bank_mask:0xf
	v_mov_b32_dpp v67, v89 row_shr:2 row_mask:0xf bank_mask:0xf
	v_mov_b32_dpp v68, v90 row_shr:2 row_mask:0xf bank_mask:0xf
	v_mov_b32_dpp v69, v91 row_shr:2 row_mask:0xf bank_mask:0xf
	v_pk_fma_f32 v[112:113], v[34:35], v[112:113], v[114:115]
	v_pk_fma_f32 v[110:111], v[32:33], v[110:111], v[116:117]
	v_pk_fma_f32 v[68:69], v[30:31], v[68:69], v[112:113]
	v_pk_fma_f32 v[66:67], v[28:29], v[66:67], v[110:111]
	v_pk_mul_f32 v[112:113], v[68:69], v[68:69]
	v_pk_mul_f32 v[110:111], v[66:67], v[66:67]
	v_pk_fma_f32 v[112:113], v[112:113], s[30:31], 1.0 op_sel_hi:[1,0,0]
	v_pk_fma_f32 v[110:111], v[110:111], s[30:31], 1.0 op_sel_hi:[1,0,0]
	v_pk_mul_f32 v[112:113], v[68:69], v[112:113]
	v_pk_mul_f32 v[110:111], v[66:67], v[110:111]
	v_pk_mul_f32 v[112:113], v[112:113], s[34:35] op_sel_hi:[1,0]
	v_pk_mul_f32 v[110:111], v[110:111], s[34:35] op_sel_hi:[1,0]
	v_exp_f32_e32 v112, v112
	v_exp_f32_e32 v110, v110
	v_exp_f32_e32 v113, v113
	v_exp_f32_e32 v111, v111
	v_mov_b32_e32 v70, v104
	v_mov_b32_e32 v71, v105
	v_mov_b32_e32 v108, v106
	v_mov_b32_e32 v109, v107
	v_pk_mul_f32 v[94:95], v[94:95], v[194:195] op_sel_hi:[1,0]
	v_pk_mul_f32 v[92:93], v[92:93], v[194:195] op_sel_hi:[1,0]
	v_mov_b32_dpp v70, v70 row_ror:1 row_mask:0xf bank_mask:0xf
	v_mov_b32_dpp v71, v71 row_ror:1 row_mask:0xf bank_mask:0xf
	v_mov_b32_dpp v108, v108 row_ror:1 row_mask:0xf bank_mask:0xf
	v_mov_b32_dpp v109, v109 row_ror:1 row_mask:0xf bank_mask:0xf
	v_mov_b32_dpp v70, v92 row_shr:1 row_mask:0xf bank_mask:0xf
	v_mov_b32_dpp v104, v104 row_ror:2 row_mask:0xf bank_mask:0xf
	v_mov_b32_dpp v71, v93 row_shr:1 row_mask:0xf bank_mask:0xf
	v_mov_b32_dpp v105, v105 row_ror:2 row_mask:0xf bank_mask:0xf
	v_mov_b32_dpp v108, v94 row_shr:1 row_mask:0xf bank_mask:0xf
	v_mov_b32_dpp v106, v106 row_ror:2 row_mask:0xf bank_mask:0xf
	v_mov_b32_dpp v109, v95 row_shr:1 row_mask:0xf bank_mask:0xf
	v_mov_b32_dpp v107, v107 row_ror:2 row_mask:0xf bank_mask:0xf
	v_pk_mul_f32 v[68:69], v[100:101], v[68:69]
	v_pk_mul_f32 v[66:67], v[102:103], v[66:67]
	v_pk_add_f32 v[100:101], v[112:113], 1.0 op_sel_hi:[1,0]
	v_pk_add_f32 v[102:103], v[110:111], 1.0 op_sel_hi:[1,0]
	v_pk_fma_f32 v[110:111], v[94:95], v[22:23], v[26:27]
	v_pk_fma_f32 v[112:113], v[92:93], v[20:21], v[24:25]
	v_mov_b32_dpp v104, v92 row_shr:2 row_mask:0xf bank_mask:0xf
	v_mov_b32_dpp v105, v93 row_shr:2 row_mask:0xf bank_mask:0xf
	v_mov_b32_dpp v106, v94 row_shr:2 row_mask:0xf bank_mask:0xf
	v_mov_b32_dpp v107, v95 row_shr:2 row_mask:0xf bank_mask:0xf
	v_pk_fma_f32 v[108:109], v[18:19], v[108:109], v[110:111]
	v_pk_fma_f32 v[70:71], v[16:17], v[70:71], v[112:113]
	v_rcp_f32_e32 v102, v102
	v_pk_fma_f32 v[70:71], v[12:13], v[104:105], v[70:71]
	v_pk_fma_f32 v[104:105], v[14:15], v[106:107], v[108:109]
	v_pk_mul_f32 v[106:107], v[70:71], v[70:71]
	v_pk_mul_f32 v[108:109], v[104:105], v[104:105]
	v_pk_fma_f32 v[106:107], v[106:107], s[30:31], 1.0 op_sel_hi:[1,0,0]
	v_pk_fma_f32 v[108:109], v[108:109], s[30:31], 1.0 op_sel_hi:[1,0,0]
	v_pk_mul_f32 v[106:107], v[70:71], v[106:107]
	v_pk_mul_f32 v[108:109], v[104:105], v[108:109]
	v_pk_mul_f32 v[106:107], v[106:107], s[34:35] op_sel_hi:[1,0]
	v_pk_mul_f32 v[108:109], v[108:109], s[34:35] op_sel_hi:[1,0]
	v_rcp_f32_e32 v103, v103
	v_rcp_f32_e32 v100, v100
	v_rcp_f32_e32 v101, v101
	v_exp_f32_e32 v106, v106
	v_exp_f32_e32 v108, v108
	v_exp_f32_e32 v109, v109
	v_exp_f32_e32 v107, v107
	v_pk_mul_f32 v[102:103], v[66:67], v[102:103]
	v_pk_mul_f32 v[100:101], v[68:69], v[100:101]
	v_pk_add_f32 v[66:67], v[108:109], 1.0 op_sel_hi:[1,0]
	v_pk_add_f32 v[68:69], v[106:107], 1.0 op_sel_hi:[1,0]
	v_rcp_f32_e32 v66, v66
	v_rcp_f32_e32 v68, v68
	v_rcp_f32_e32 v69, v69
	v_rcp_f32_e32 v67, v67
	v_pk_mul_f32 v[96:97], v[96:97], v[104:105]
	v_pk_mul_f32 v[70:71], v[98:99], v[70:71]
	v_pk_fma_f32 v[98:99], v[78:79], v[38:39], v[42:43]
	v_pk_mul_f32 v[68:69], v[70:71], v[68:69]
	v_pk_mul_f32 v[70:71], v[96:97], v[66:67]
	v_cvt_pk_bf16_f32 v66, v68, v69
	v_mov_b32_e32 v96, v90
	v_cvt_pk_bf16_f32 v67, v70, v71
	v_mov_b32_e32 v70, v88
	v_mov_b32_e32 v71, v89
	v_mov_b32_e32 v97, v91
	v_mov_b32_dpp v70, v70 row_ror:1 row_mask:0xf bank_mask:0xf
	v_mov_b32_dpp v71, v71 row_ror:1 row_mask:0xf bank_mask:0xf
	v_mov_b32_dpp v96, v96 row_ror:1 row_mask:0xf bank_mask:0xf
	v_mov_b32_dpp v97, v97 row_ror:1 row_mask:0xf bank_mask:0xf
	v_cvt_pk_bf16_f32 v68, v102, v103
	v_cvt_pk_bf16_f32 v69, v100, v101
	v_mov_b32_dpp v70, v76 row_shr:1 row_mask:0xf bank_mask:0xf
	v_mov_b32_dpp v88, v88 row_ror:2 row_mask:0xf bank_mask:0xf
	v_mov_b32_dpp v71, v77 row_shr:1 row_mask:0xf bank_mask:0xf
	v_mov_b32_dpp v89, v89 row_ror:2 row_mask:0xf bank_mask:0xf
	v_mov_b32_dpp v96, v78 row_shr:1 row_mask:0xf bank_mask:0xf
	v_mov_b32_dpp v90, v90 row_ror:2 row_mask:0xf bank_mask:0xf
	v_mov_b32_dpp v97, v79 row_shr:1 row_mask:0xf bank_mask:0xf
	v_mov_b32_dpp v91, v91 row_ror:2 row_mask:0xf bank_mask:0xf
	v_pk_fma_f32 v[100:101], v[76:77], v[36:37], v[40:41]
	v_mov_b32_dpp v88, v76 row_shr:2 row_mask:0xf bank_mask:0xf
	v_mov_b32_dpp v89, v77 row_shr:2 row_mask:0xf bank_mask:0xf
	v_mov_b32_dpp v90, v78 row_shr:2 row_mask:0xf bank_mask:0xf
	v_mov_b32_dpp v91, v79 row_shr:2 row_mask:0xf bank_mask:0xf
	v_pk_fma_f32 v[96:97], v[34:35], v[96:97], v[98:99]
	v_pk_fma_f32 v[70:71], v[32:33], v[70:71], v[100:101]
	v_pk_fma_f32 v[90:91], v[30:31], v[90:91], v[96:97]
	v_pk_fma_f32 v[70:71], v[28:29], v[88:89], v[70:71]
	v_pk_mul_f32 v[88:89], v[90:91], v[90:91]
	v_pk_mul_f32 v[96:97], v[70:71], v[70:71]
	v_pk_fma_f32 v[88:89], v[88:89], s[30:31], 1.0 op_sel_hi:[1,0,0]
	v_pk_fma_f32 v[96:97], v[96:97], s[30:31], 1.0 op_sel_hi:[1,0,0]
	v_pk_mul_f32 v[88:89], v[90:91], v[88:89]
	v_pk_mul_f32 v[96:97], v[70:71], v[96:97]
	v_pk_mul_f32 v[88:89], v[88:89], s[34:35] op_sel_hi:[1,0]
	v_pk_mul_f32 v[96:97], v[96:97], s[34:35] op_sel_hi:[1,0]
	v_exp_f32_e32 v88, v88
	v_exp_f32_e32 v96, v96
	v_exp_f32_e32 v89, v89
	v_exp_f32_e32 v97, v97
	v_add_u32_e32 v65, 0xb0000, v64
	global_store_dwordx4 v65, v[66:69], s[18:19] nt
	v_pk_mul_f32 v[84:85], v[84:85], v[90:91]
	v_pk_mul_f32 v[70:71], v[86:87], v[70:71]
	v_mov_b32_e32 v66, v92
	v_mov_b32_e32 v67, v93
	v_mov_b32_e32 v68, v94
	v_mov_b32_e32 v69, v95
	v_mov_b32_dpp v66, v66 row_ror:1 row_mask:0xf bank_mask:0xf
	v_mov_b32_dpp v67, v67 row_ror:1 row_mask:0xf bank_mask:0xf
	v_mov_b32_dpp v68, v68 row_ror:1 row_mask:0xf bank_mask:0xf
	v_mov_b32_dpp v69, v69 row_ror:1 row_mask:0xf bank_mask:0xf
	v_mov_b32_dpp v66, v72 row_shr:1 row_mask:0xf bank_mask:0xf
	v_mov_b32_dpp v92, v92 row_ror:2 row_mask:0xf bank_mask:0xf
	v_mov_b32_dpp v67, v73 row_shr:1 row_mask:0xf bank_mask:0xf
	v_mov_b32_dpp v93, v93 row_ror:2 row_mask:0xf bank_mask:0xf
	v_mov_b32_dpp v68, v74 row_shr:1 row_mask:0xf bank_mask:0xf
	v_mov_b32_dpp v94, v94 row_ror:2 row_mask:0xf bank_mask:0xf
	v_mov_b32_dpp v69, v75 row_shr:1 row_mask:0xf bank_mask:0xf
	v_mov_b32_dpp v95, v95 row_ror:2 row_mask:0xf bank_mask:0xf
	v_pk_add_f32 v[86:87], v[88:89], 1.0 op_sel_hi:[1,0]
	v_pk_add_f32 v[88:89], v[96:97], 1.0 op_sel_hi:[1,0]
	v_pk_fma_f32 v[90:91], v[74:75], v[22:23], v[26:27]
	v_pk_fma_f32 v[96:97], v[72:73], v[20:21], v[24:25]
	v_mov_b32_dpp v92, v72 row_shr:2 row_mask:0xf bank_mask:0xf
	v_mov_b32_dpp v93, v73 row_shr:2 row_mask:0xf bank_mask:0xf
	v_mov_b32_dpp v94, v74 row_shr:2 row_mask:0xf bank_mask:0xf
	v_mov_b32_dpp v95, v75 row_shr:2 row_mask:0xf bank_mask:0xf
	v_pk_fma_f32 v[68:69], v[18:19], v[68:69], v[90:91]
	v_pk_fma_f32 v[66:67], v[16:17], v[66:67], v[96:97]
	v_pk_fma_f32 v[68:69], v[14:15], v[94:95], v[68:69]
	v_pk_fma_f32 v[66:67], v[12:13], v[92:93], v[66:67]
	v_pk_mul_f32 v[90:91], v[68:69], v[68:69]
	v_pk_mul_f32 v[92:93], v[66:67], v[66:67]
	v_pk_fma_f32 v[90:91], v[90:91], s[30:31], 1.0 op_sel_hi:[1,0,0]
	v_pk_fma_f32 v[92:93], v[92:93], s[30:31], 1.0 op_sel_hi:[1,0,0]
	v_pk_mul_f32 v[90:91], v[68:69], v[90:91]
	v_pk_mul_f32 v[92:93], v[66:67], v[92:93]
	v_pk_mul_f32 v[90:91], v[90:91], s[34:35] op_sel_hi:[1,0]
	v_pk_mul_f32 v[92:93], v[92:93], s[34:35] op_sel_hi:[1,0]
	v_rcp_f32_e32 v88, v88
	v_rcp_f32_e32 v89, v89
	v_rcp_f32_e32 v86, v86
	v_rcp_f32_e32 v87, v87
	v_exp_f32_e32 v92, v92
	v_exp_f32_e32 v90, v90
	v_exp_f32_e32 v91, v91
	v_exp_f32_e32 v93, v93
	v_pk_mul_f32 v[84:85], v[84:85], v[86:87]
	v_pk_mul_f32 v[70:71], v[70:71], v[88:89]
	v_pk_add_f32 v[86:87], v[90:91], 1.0 op_sel_hi:[1,0]
	v_pk_add_f32 v[88:89], v[92:93], 1.0 op_sel_hi:[1,0]
	v_rcp_f32_e32 v86, v86
	v_rcp_f32_e32 v88, v88
	v_rcp_f32_e32 v87, v87
	v_rcp_f32_e32 v89, v89
	v_pk_mul_f32 v[68:69], v[80:81], v[68:69]
	v_pk_mul_f32 v[66:67], v[82:83], v[66:67]
	v_pk_mul_f32 v[68:69], v[68:69], v[86:87]
	v_pk_mul_f32 v[66:67], v[66:67], v[88:89]
	v_mov_b32_e32 v80, v78
	v_cvt_pk_bf16_f32 v66, v66, v67
	v_cvt_pk_bf16_f32 v67, v68, v69
	v_cvt_pk_bf16_f32 v68, v70, v71
	v_mov_b32_e32 v70, v76
	v_mov_b32_e32 v71, v77
	v_mov_b32_e32 v81, v79
	v_mov_b32_dpp v70, v70 row_ror:1 row_mask:0xf bank_mask:0xf
	v_mov_b32_dpp v71, v71 row_ror:1 row_mask:0xf bank_mask:0xf
	v_mov_b32_dpp v80, v80 row_ror:1 row_mask:0xf bank_mask:0xf
	v_mov_b32_dpp v81, v81 row_ror:1 row_mask:0xf bank_mask:0xf
	v_cvt_pk_bf16_f32 v69, v84, v85
	v_mov_b32_dpp v70, v60 row_shr:1 row_mask:0xf bank_mask:0xf
	v_mov_b32_dpp v76, v76 row_ror:2 row_mask:0xf bank_mask:0xf
	v_mov_b32_dpp v71, v61 row_shr:1 row_mask:0xf bank_mask:0xf
	v_mov_b32_dpp v77, v77 row_ror:2 row_mask:0xf bank_mask:0xf
	v_mov_b32_dpp v80, v62 row_shr:1 row_mask:0xf bank_mask:0xf
	v_mov_b32_dpp v78, v78 row_ror:2 row_mask:0xf bank_mask:0xf
	v_mov_b32_dpp v81, v63 row_shr:1 row_mask:0xf bank_mask:0xf
	v_mov_b32_dpp v79, v79 row_ror:2 row_mask:0xf bank_mask:0xf
	v_pk_fma_f32 v[82:83], v[62:63], v[38:39], v[42:43]
	v_pk_fma_f32 v[84:85], v[60:61], v[36:37], v[40:41]
	v_mov_b32_dpp v76, v60 row_shr:2 row_mask:0xf bank_mask:0xf
	v_mov_b32_dpp v77, v61 row_shr:2 row_mask:0xf bank_mask:0xf
	v_mov_b32_dpp v78, v62 row_shr:2 row_mask:0xf bank_mask:0xf
	v_mov_b32_dpp v79, v63 row_shr:2 row_mask:0xf bank_mask:0xf
	v_pk_fma_f32 v[80:81], v[34:35], v[80:81], v[82:83]
	v_pk_fma_f32 v[70:71], v[32:33], v[70:71], v[84:85]
	v_pk_fma_f32 v[78:79], v[30:31], v[78:79], v[80:81]
	v_pk_fma_f32 v[70:71], v[28:29], v[76:77], v[70:71]
	v_pk_mul_f32 v[76:77], v[78:79], v[78:79]
	v_pk_mul_f32 v[80:81], v[70:71], v[70:71]
	v_pk_fma_f32 v[76:77], v[76:77], s[30:31], 1.0 op_sel_hi:[1,0,0]
	v_pk_fma_f32 v[80:81], v[80:81], s[30:31], 1.0 op_sel_hi:[1,0,0]
	v_pk_mul_f32 v[76:77], v[78:79], v[76:77]
	v_pk_mul_f32 v[80:81], v[70:71], v[80:81]
	v_pk_mul_f32 v[76:77], v[76:77], s[34:35] op_sel_hi:[1,0]
	v_pk_mul_f32 v[80:81], v[80:81], s[34:35] op_sel_hi:[1,0]
	v_exp_f32_e32 v76, v76
	v_exp_f32_e32 v80, v80
	v_exp_f32_e32 v77, v77
	v_exp_f32_e32 v81, v81
	v_add_u32_e32 v65, 0xc6000, v64
	global_store_dwordx4 v65, v[66:69], s[18:19] nt
	v_pk_mul_f32 v[50:51], v[50:51], v[186:187] op_sel_hi:[1,0]
	v_pk_mul_f32 v[48:49], v[48:49], v[186:187] op_sel_hi:[1,0]
	v_mov_b32_e32 v66, v72
	v_mov_b32_e32 v67, v73
	v_mov_b32_e32 v68, v74
	v_mov_b32_e32 v69, v75
	v_mov_b32_dpp v66, v66 row_ror:1 row_mask:0xf bank_mask:0xf
	v_mov_b32_dpp v67, v67 row_ror:1 row_mask:0xf bank_mask:0xf
	v_mov_b32_dpp v68, v68 row_ror:1 row_mask:0xf bank_mask:0xf
	v_mov_b32_dpp v69, v69 row_ror:1 row_mask:0xf bank_mask:0xf
	v_mov_b32_dpp v66, v56 row_shr:1 row_mask:0xf bank_mask:0xf
	v_mov_b32_dpp v72, v72 row_ror:2 row_mask:0xf bank_mask:0xf
	v_mov_b32_dpp v67, v57 row_shr:1 row_mask:0xf bank_mask:0xf
	v_mov_b32_dpp v73, v73 row_ror:2 row_mask:0xf bank_mask:0xf
	v_mov_b32_dpp v68, v58 row_shr:1 row_mask:0xf bank_mask:0xf
	v_mov_b32_dpp v74, v74 row_ror:2 row_mask:0xf bank_mask:0xf
	v_mov_b32_dpp v69, v59 row_shr:1 row_mask:0xf bank_mask:0xf
	v_mov_b32_dpp v75, v75 row_ror:2 row_mask:0xf bank_mask:0xf
	v_pk_mul_f32 v[50:51], v[50:51], v[78:79]
	v_pk_mul_f32 v[48:49], v[48:49], v[70:71]
	v_pk_add_f32 v[70:71], v[76:77], 1.0 op_sel_hi:[1,0]
	v_pk_add_f32 v[76:77], v[80:81], 1.0 op_sel_hi:[1,0]
	v_pk_fma_f32 v[78:79], v[58:59], v[22:23], v[26:27]
	v_pk_fma_f32 v[80:81], v[56:57], v[20:21], v[24:25]
	v_mov_b32_dpp v72, v56 row_shr:2 row_mask:0xf bank_mask:0xf
	v_mov_b32_dpp v73, v57 row_shr:2 row_mask:0xf bank_mask:0xf
	v_mov_b32_dpp v74, v58 row_shr:2 row_mask:0xf bank_mask:0xf
	v_mov_b32_dpp v75, v59 row_shr:2 row_mask:0xf bank_mask:0xf
	v_pk_fma_f32 v[68:69], v[18:19], v[68:69], v[78:79]
	v_pk_fma_f32 v[66:67], v[16:17], v[66:67], v[80:81]
	v_pk_fma_f32 v[68:69], v[14:15], v[74:75], v[68:69]
	v_pk_fma_f32 v[66:67], v[12:13], v[72:73], v[66:67]
	v_pk_mul_f32 v[72:73], v[68:69], v[68:69]
	v_pk_mul_f32 v[74:75], v[66:67], v[66:67]
	v_pk_fma_f32 v[72:73], v[72:73], s[30:31], 1.0 op_sel_hi:[1,0,0]
	v_pk_fma_f32 v[74:75], v[74:75], s[30:31], 1.0 op_sel_hi:[1,0,0]
	v_pk_mul_f32 v[72:73], v[68:69], v[72:73]
	v_pk_mul_f32 v[74:75], v[66:67], v[74:75]
	v_pk_mul_f32 v[72:73], v[72:73], s[34:35] op_sel_hi:[1,0]
	v_pk_mul_f32 v[74:75], v[74:75], s[34:35] op_sel_hi:[1,0]
	v_rcp_f32_e32 v76, v76
	v_rcp_f32_e32 v77, v77
	v_rcp_f32_e32 v70, v70
	v_rcp_f32_e32 v71, v71
	v_exp_f32_e32 v74, v74
	v_exp_f32_e32 v72, v72
	v_exp_f32_e32 v73, v73
	v_exp_f32_e32 v75, v75
	v_pk_mul_f32 v[70:71], v[50:51], v[70:71]
	v_pk_mul_f32 v[50:51], v[48:49], v[76:77]
	v_pk_add_f32 v[48:49], v[72:73], 1.0 op_sel_hi:[1,0]
	v_pk_add_f32 v[72:73], v[74:75], 1.0 op_sel_hi:[1,0]
	v_rcp_f32_e32 v48, v48
	v_rcp_f32_e32 v72, v72
	v_rcp_f32_e32 v49, v49
	v_rcp_f32_e32 v73, v73
	v_pk_mul_f32 v[54:55], v[54:55], v[186:187] op_sel_hi:[1,0]
	v_pk_mul_f32 v[52:53], v[52:53], v[186:187] op_sel_hi:[1,0]
	v_pk_mul_f32 v[54:55], v[54:55], v[68:69]
	v_pk_mul_f32 v[52:53], v[52:53], v[66:67]
	v_pk_mul_f32 v[54:55], v[54:55], v[48:49]
	v_pk_mul_f32 v[48:49], v[52:53], v[72:73]
	v_add_u32_e32 v52, 0xdc000, v64
	v_cvt_pk_bf16_f32 v48, v48, v49
	v_cvt_pk_bf16_f32 v49, v54, v55
	v_cvt_pk_bf16_f32 v50, v50, v51
	v_cvt_pk_bf16_f32 v51, v70, v71
	global_store_dwordx4 v52, v[48:51], s[18:19] nt
	v_mov_b32_e32 v52, v60
	v_mov_b32_e32 v53, v61
	v_mov_b32_e32 v54, v62
	v_mov_b32_e32 v55, v63
	v_mov_b32_dpp v52, v52 row_ror:1 row_mask:0xf bank_mask:0xf
	v_mov_b32_dpp v60, v60 row_ror:2 row_mask:0xf bank_mask:0xf
	v_mov_b32_dpp v53, v53 row_ror:1 row_mask:0xf bank_mask:0xf
	v_mov_b32_dpp v61, v61 row_ror:2 row_mask:0xf bank_mask:0xf
	v_mov_b32_dpp v54, v54 row_ror:1 row_mask:0xf bank_mask:0xf
	v_mov_b32_dpp v62, v62 row_ror:2 row_mask:0xf bank_mask:0xf
	v_mov_b32_dpp v55, v55 row_ror:1 row_mask:0xf bank_mask:0xf
	v_mov_b32_dpp v63, v63 row_ror:2 row_mask:0xf bank_mask:0xf
	v_mov_b32_dpp v52, v8 row_shr:1 row_mask:0xf bank_mask:0xf
	v_mov_b32_dpp v60, v8 row_shr:2 row_mask:0xf bank_mask:0xf
	v_mov_b32_dpp v53, v9 row_shr:1 row_mask:0xf bank_mask:0xf
	v_mov_b32_dpp v61, v9 row_shr:2 row_mask:0xf bank_mask:0xf
	v_mov_b32_dpp v54, v10 row_shr:1 row_mask:0xf bank_mask:0xf
	v_mov_b32_dpp v62, v10 row_shr:2 row_mask:0xf bank_mask:0xf
	v_mov_b32_dpp v55, v11 row_shr:1 row_mask:0xf bank_mask:0xf
	v_mov_b32_dpp v63, v11 row_shr:2 row_mask:0xf bank_mask:0xf
	v_pk_fma_f32 v[10:11], v[10:11], v[38:39], v[42:43]
	v_pk_fma_f32 v[8:9], v[8:9], v[36:37], v[40:41]
	v_pk_fma_f32 v[10:11], v[34:35], v[54:55], v[10:11]
	v_pk_fma_f32 v[8:9], v[32:33], v[52:53], v[8:9]
	v_pk_fma_f32 v[10:11], v[30:31], v[62:63], v[10:11]
	v_pk_fma_f32 v[8:9], v[28:29], v[60:61], v[8:9]
	v_mov_b32_e32 v48, v56
	v_mov_b32_e32 v49, v57
	v_mov_b32_e32 v50, v58
	v_mov_b32_e32 v51, v59
	v_pk_mul_f32 v[28:29], v[10:11], v[10:11]
	v_pk_mul_f32 v[30:31], v[8:9], v[8:9]
	v_mov_b32_dpp v48, v48 row_ror:1 row_mask:0xf bank_mask:0xf
	v_mov_b32_dpp v56, v56 row_ror:2 row_mask:0xf bank_mask:0xf
	v_mov_b32_dpp v49, v49 row_ror:1 row_mask:0xf bank_mask:0xf
	v_mov_b32_dpp v57, v57 row_ror:2 row_mask:0xf bank_mask:0xf
	v_mov_b32_dpp v50, v50 row_ror:1 row_mask:0xf bank_mask:0xf
	v_mov_b32_dpp v58, v58 row_ror:2 row_mask:0xf bank_mask:0xf
	v_mov_b32_dpp v51, v51 row_ror:1 row_mask:0xf bank_mask:0xf
	v_mov_b32_dpp v59, v59 row_ror:2 row_mask:0xf bank_mask:0xf
	v_pk_fma_f32 v[28:29], v[28:29], s[30:31], 1.0 op_sel_hi:[1,0,0]
	v_pk_fma_f32 v[30:31], v[30:31], s[30:31], 1.0 op_sel_hi:[1,0,0]
	v_mov_b32_dpp v48, v4 row_shr:1 row_mask:0xf bank_mask:0xf
	v_mov_b32_dpp v56, v4 row_shr:2 row_mask:0xf bank_mask:0xf
	v_mov_b32_dpp v49, v5 row_shr:1 row_mask:0xf bank_mask:0xf
	v_mov_b32_dpp v57, v5 row_shr:2 row_mask:0xf bank_mask:0xf
	v_mov_b32_dpp v50, v6 row_shr:1 row_mask:0xf bank_mask:0xf
	v_mov_b32_dpp v58, v6 row_shr:2 row_mask:0xf bank_mask:0xf
	v_mov_b32_dpp v51, v7 row_shr:1 row_mask:0xf bank_mask:0xf
	v_mov_b32_dpp v59, v7 row_shr:2 row_mask:0xf bank_mask:0xf
	v_pk_mul_f32 v[28:29], v[10:11], v[28:29]
	v_pk_mul_f32 v[30:31], v[8:9], v[30:31]
	v_pk_fma_f32 v[6:7], v[6:7], v[22:23], v[26:27]
	v_pk_fma_f32 v[4:5], v[4:5], v[20:21], v[24:25]
	v_pk_mul_f32 v[28:29], v[28:29], s[34:35] op_sel_hi:[1,0]
	v_pk_mul_f32 v[30:31], v[30:31], s[34:35] op_sel_hi:[1,0]
	v_pk_fma_f32 v[6:7], v[18:19], v[50:51], v[6:7]
	v_pk_fma_f32 v[4:5], v[16:17], v[48:49], v[4:5]
	v_exp_f32_e32 v30, v30
	v_exp_f32_e32 v28, v28
	v_exp_f32_e32 v29, v29
	v_exp_f32_e32 v31, v31
	v_pk_fma_f32 v[6:7], v[14:15], v[58:59], v[6:7]
	v_pk_fma_f32 v[4:5], v[12:13], v[56:57], v[4:5]
	v_pk_mul_f32 v[12:13], v[6:7], v[6:7]
	v_pk_mul_f32 v[14:15], v[4:5], v[4:5]
	v_mov_b32_e32 v183, v182
	v_pk_fma_f32 v[12:13], v[12:13], s[30:31], 1.0 op_sel_hi:[1,0,0]
	v_pk_fma_f32 v[14:15], v[14:15], s[30:31], 1.0 op_sel_hi:[1,0,0]
	v_pk_mul_f32 v[0:1], v[0:1], v[182:183]
	v_pk_mul_f32 v[12:13], v[6:7], v[12:13]
	v_pk_mul_f32 v[14:15], v[4:5], v[14:15]
	v_pk_mul_f32 v[2:3], v[2:3], v[10:11]
	v_pk_mul_f32 v[0:1], v[0:1], v[8:9]
	v_pk_add_f32 v[8:9], v[28:29], 1.0 op_sel_hi:[1,0]
	v_pk_add_f32 v[10:11], v[30:31], 1.0 op_sel_hi:[1,0]
	v_pk_mul_f32 v[12:13], v[12:13], s[34:35] op_sel_hi:[1,0]
	v_pk_mul_f32 v[14:15], v[14:15], s[34:35] op_sel_hi:[1,0]
	v_rcp_f32_e32 v10, v10
	v_rcp_f32_e32 v11, v11
	v_rcp_f32_e32 v8, v8
	v_rcp_f32_e32 v9, v9
	v_exp_f32_e32 v14, v14
	v_exp_f32_e32 v12, v12
	v_exp_f32_e32 v13, v13
	v_exp_f32_e32 v15, v15
	v_pk_mul_f32 v[8:9], v[2:3], v[8:9]
	v_pk_mul_f32 v[2:3], v[0:1], v[10:11]
	v_pk_add_f32 v[0:1], v[12:13], 1.0 op_sel_hi:[1,0]
	v_pk_add_f32 v[10:11], v[14:15], 1.0 op_sel_hi:[1,0]
	v_rcp_f32_e32 v0, v0
	v_rcp_f32_e32 v10, v10
	v_rcp_f32_e32 v1, v1
	v_rcp_f32_e32 v11, v11
	v_pk_mul_f32 v[44:45], v[44:45], v[182:183]
	v_pk_mul_f32 v[6:7], v[46:47], v[6:7]
	v_pk_mul_f32 v[4:5], v[44:45], v[4:5]
	v_pk_mul_f32 v[6:7], v[6:7], v[0:1]
	v_pk_mul_f32 v[0:1], v[4:5], v[10:11]
	v_add_u32_e32 v4, 0xf2000, v64
	s_cmp_eq_u32 s65, s76
	s_mov_b64 s[54:55], -1
	v_cvt_pk_bf16_f32 v0, v0, v1
	v_cvt_pk_bf16_f32 v1, v6, v7
	v_cvt_pk_bf16_f32 v2, v2, v3
	v_cvt_pk_bf16_f32 v3, v8, v9
	global_store_dwordx4 v4, v[0:3], s[18:19] nt
	s_cbranch_scc1 .LBB0_1250
	s_and_b64 vcc, exec, s[4:5]
	s_cbranch_vccnz .LBB0_1249
	s_barrier
	s_branch .LBB0_1249
